# band items: tile order 1,2,(0|3) - three steps instead of four (waves 0-1 take tile 0 and waves 2-3 tile 3 in the last step), on top of previous
# speedup vs baseline: 1.0384x; 1.0026x over previous
; DI void band_item(const Params& P, char* lds_blk, int layer, int bp) {
;     ...
;     const int maxd = type == 0 ? 127 : 128;
;     const int qpos = 128 + 32 * w + r;
;     const int kt0 = (nb == 0 ? 2 : 0);
;     u32x4 rk[2], rv[2];
;     const int srow = tid >> 3, sch = tid & 7;
;     auto gload = [&](int kt) {
; #pragma unroll
;         for (int j = 0; j < 2; ++j) {
;             const ptrdiff_t ro = ((ptrdiff_t)(64 * kt + srow + 32 * j) - 128) * (ptrdiff_t)rs + sch * 8;
;             rk[j] = *(const u32x4*)(kp + ro); rv[j] = *(const u32x4*)(vp + ro);
;         }
;     };
;     auto lstore = [&](int b) {
;         char* sK = lds + b * (2 * 64 * GP); char* sV = sK + 64 * GP;
; #pragma unroll
;         for (int j = 0; j < 2; ++j) { *(u32x4*)(sK + (srow + 32 * j) * GP + sch * 16) = rk[j]; *(u32x4*)(sV + (srow + 32 * j) * GP + sch * 16) = rv[j]; }
;     };
;     gload(kt0); lstore(0);
.LBB0_212:
	s_cmp_eq_u32 s64, 0
	s_cselect_b32 s1, 2, 1
	s_cselect_b32 s100, 0, 1
	v_lshrrev_b32_sdwa v0, v191, v10 dst_sel:DWORD dst_unused:UNUSED_PAD src0_sel:DWORD src1_sel:BYTE_0
	s_lshl_b32 s64, s1, 6
	v_or_b32_e32 v15, s64, v0
	v_and_b32_e32 v113, 7, v10
	v_add_u32_e32 v3, 0xffffff80, v15
	v_mul_hi_i32_i24_e32 v13, s72, v3
	v_mul_i32_i24_e32 v12, s72, v3
	v_lshlrev_b32_e32 v110, 3, v113
	s_lshl_b32 s16, s72, 5
	v_ashrrev_i32_e32 v5, 31, v4
	v_or_b32_e32 v20, v12, v110
	v_mov_b32_e32 v21, v13
	v_lshl_add_u64 v[12:13], v[12:13], 0, s[16:17]
	v_ashrrev_i32_e32 v7, 31, v6
	v_lshlrev_b64 v[16:17], 1, v[4:5]
	v_or_b32_e32 v12, v12, v110
	v_lshl_add_u64 v[4:5], s[22:23], 0, v[16:17]
	v_lshlrev_b64 v[18:19], 1, v[6:7]
	v_lshlrev_b64 v[20:21], 1, v[20:21]
	v_lshlrev_b64 v[12:13], 1, v[12:13]
	v_lshl_add_u64 v[6:7], s[22:23], 0, v[18:19]
	v_lshl_add_u64 v[22:23], v[4:5], 0, v[20:21]
	v_lshl_add_u64 v[4:5], v[4:5], 0, v[12:13]
	v_lshl_add_u64 v[20:21], v[6:7], 0, v[20:21]
	flat_load_dwordx4 v[82:85], v[22:23]
	flat_load_dwordx4 v[86:89], v[20:21]
	v_lshl_add_u64 v[6:7], v[6:7], 0, v[12:13]
	flat_load_dwordx4 v[90:93], v[4:5]
	flat_load_dwordx4 v[94:97], v[6:7]
	v_add_u32_e32 v20, s0, v111
	v_lshlrev_b32_e32 v21, 2, v8
	v_lshrrev_b32_e32 v23, 2, v10
	v_add_u32_e32 v26, v111, v123
	s_add_i32 s0, s70, s65
	v_or_b32_e32 v22, 32, v107
	v_and_b32_e32 v24, 16, v10
	v_lshlrev_b32_e32 v25, 2, v107
	v_add_u32_e32 v128, 0x80, v20
	v_and_or_b32 v20, v23, 3, v21
	v_sub_u32_e32 v21, v26, v21
	s_add_i32 s0, s0, s71
	v_mul_u32_u24_e32 v129, 0x90, v22
	v_and_or_b32 v22, v25, 12, v24
	v_mul_u32_u24_e32 v131, 0x90, v20
	s_add_i32 s65, s1, -1
	v_subrev_u32_e32 v20, s64, v21
	s_mul_hi_u32 s1, s0, 0x3800
	s_mulk_i32 s0, 0x3800
	s_lshl_b32 s16, s72, 1
	v_lshlrev_b32_e32 v132, 1, v22
	v_lshlrev_b32_e32 v22, 2, v20
	v_subrev_u32_e32 v23, 32, v15
	v_mov_b64_e32 v[20:21], s[0:1]
	v_subrev_u32_e32 v24, 64, v15
	v_add_u32_e32 v125, 0, v14
	v_add3_u32 v134, v14, v22, s44
	v_mad_i64_i32 v[14:15], s[0:1], s16, v23, v[20:21]
	v_mad_i64_i32 v[20:21], s[0:1], s16, v24, v[20:21]
	v_mul_u32_u24_e32 v27, 0x90, v0
	v_lshlrev_b32_e32 v0, 4, v113
	v_lshl_add_u64 v[22:23], v[14:15], 0, v[18:19]
	v_lshl_add_u64 v[14:15], v[14:15], 0, v[16:17]
	v_lshl_add_u64 v[18:19], v[20:21], 0, v[18:19]
	v_lshl_add_u64 v[16:17], v[20:21], 0, v[16:17]
	v_or_b32_e32 v126, 0x9f, v111
	v_mul_u32_u24_e32 v127, 0x90, v123
	v_mov_b32_e32 v3, v2
	v_mov_b32_e32 v4, v2
	v_mov_b32_e32 v5, v2
	v_mov_b32_e32 v6, v2
	v_mov_b32_e32 v7, v2
	v_mov_b32_e32 v8, v2
	v_mov_b32_e32 v9, v2
	v_mov_b32_e32 v10, v2
	v_mov_b32_e32 v11, v2
	v_mov_b32_e32 v12, v2
	v_mov_b32_e32 v13, v2
	v_add3_u32 v130, v125, v27, v0
	s_lshl_b32 s16, s72, 7
	v_lshl_add_u64 v[114:115], s[34:35], 0, v[22:23]
	v_lshl_add_u64 v[116:117], s[34:35], 0, v[14:15]
	v_lshl_add_u64 v[118:119], s[34:35], 0, v[18:19]
	v_lshl_add_u64 v[120:121], s[34:35], 0, v[16:17]
	v_mov_b32_e32 v14, v2
	v_mov_b32_e32 v15, v2
	v_mov_b32_e32 v16, v2
	v_mov_b32_e32 v17, v2
	v_mov_b32_e32 v18, v2
	v_mov_b32_e32 v19, v2
	v_mov_b32_e32 v20, v2
	v_mov_b32_e32 v21, v2
	v_mov_b32_e32 v22, v2
	v_mov_b32_e32 v23, v2
	v_mov_b32_e32 v24, v2
	v_mov_b32_e32 v25, v2
	v_mov_b32_e32 v26, v2
	v_mov_b32_e32 v27, v2
	v_mov_b32_e32 v28, v2
	v_mov_b32_e32 v29, v2
	v_mov_b32_e32 v30, v2
	v_mov_b32_e32 v31, v2
	v_mov_b32_e32 v32, v2
	v_mov_b32_e32 v33, v2
	s_waitcnt vmcnt(0) lgkmcnt(0)
	s_cmp_eq_u32 s65, 0
	s_cselect_b32 s0, 0x4800, 0
	v_add_u32_e32 v254, s0, v130
	ds_write_b128 v254, v[82:85]
	ds_write_b128 v254, v[86:89] offset:9216
	ds_write_b128 v254, v[90:93] offset:4608
	ds_write_b128 v254, v[94:97] offset:13824
	s_branch .LBB0_214

; #define LAS __attribute__((address_space(3)))
; #define MFMA(a, b, c) __builtin_amdgcn_mfma_f32_32x32x16_bf16((a), (b), (c), 0, 0, 0)
; template <int DVT>
; DI void attn_step(lptr sKw, int kpitch, lptr sV, int vpitch, const bf16x8 (&qf)[4], float& m, float& l, f32x16 (&O)[DVT],
;                   const LAS float* tb, bool far, float cfar, int lane) {
;     ...
;     for (int s = 0; s < 4; ++s) {
;         kf[2 * s] = *(const LAS bf16x8*)(sKw + r * kpitch + (16 * s + 8 * h) * 2);
;         kf[2 * s + 1] = *(const LAS bf16x8*)(sKw + (32 + r) * kpitch + (16 * s + 8 * h) * 2);
;     }
;     __builtin_amdgcn_sched_barrier(0);
; #pragma unroll
;     for (int s = 0; s < 4; ++s) { p0 = MFMA(kf[2 * s], qf[s], p0); p1 = MFMA(kf[2 * s + 1], qf[s], p1); }
; DI void band_item(const Params& P, char* lds_blk, int layer, int bp) {
;     ...
;     for (int kt = kt0; kt < 4; ++kt) {
;         if (kt + 1 < 4) gload(kt + 1);
;         __syncthreads();
;         const int b = (kt - kt0) & 1;
;         const bool active = (64 * kt <= 128 + 32 * w + 31) && (64 * kt + 63 >= 128 + 32 * w - maxd);
;         if (active) {
;             const LAS float* tb = (const LAS float*)btab + (qpos - 64 * kt - 4 * h + 128 - 63);
;             lptr sK = (lptr)lds + b * (2 * 64 * GP);
;             attn_step<2>(sK, GP, sK + 64 * GP, GP, qf, m, l, O, tb, false, 0.f, lane);
.LBB0_214:
	s_cmp_lg_u32 s65, 2
	s_cselect_b64 s[22:23], -1, 0
	s_cmp_eq_u32 s65, 2
	s_cbranch_scc1 .LBB0_216
	v_lshl_add_u64 v[34:35], v[120:121], 0, v[0:1]
	s_waitcnt vmcnt(0)
	flat_load_dwordx4 v[82:85], v[34:35]
	v_lshl_add_u64 v[34:35], v[118:119], 0, v[0:1]
	flat_load_dwordx4 v[86:89], v[34:35]
	v_lshl_add_u64 v[34:35], v[116:117], 0, v[0:1]
	flat_load_dwordx4 v[90:93], v[34:35]
	v_lshl_add_u64 v[34:35], v[114:115], 0, v[0:1]
	flat_load_dwordx4 v[94:97], v[34:35]
	s_cmp_eq_u32 s65, 1
	s_cbranch_scc0 .Lb3_no0
	s_cmp_eq_u32 s100, 1
	s_cbranch_scc0 .Lb3_no0
	s_mul_i32 s0, s16, 3
	v_lshl_add_u64 v[34:35], v[120:121], 0, v[0:1]
	v_subrev_co_u32_e32 v254, vcc, s0, v34
	s_nop 1
	v_subbrev_co_u32_e32 v255, vcc, 0, v35, vcc
	global_load_dwordx4 v[238:241], v[254:255], off
	v_lshl_add_u64 v[34:35], v[118:119], 0, v[0:1]
	v_subrev_co_u32_e32 v254, vcc, s0, v34
	s_nop 1
	v_subbrev_co_u32_e32 v255, vcc, 0, v35, vcc
	global_load_dwordx4 v[242:245], v[254:255], off
	v_lshl_add_u64 v[34:35], v[116:117], 0, v[0:1]
	v_subrev_co_u32_e32 v254, vcc, s0, v34
	s_nop 1
	v_subbrev_co_u32_e32 v255, vcc, 0, v35, vcc
	global_load_dwordx4 v[246:249], v[254:255], off
	v_lshl_add_u64 v[34:35], v[114:115], 0, v[0:1]
	v_subrev_co_u32_e32 v254, vcc, s0, v34
	s_nop 1
	v_subbrev_co_u32_e32 v255, vcc, 0, v35, vcc
	global_load_dwordx4 v[250:253], v[254:255], off
.Lb3_no0:
.LBB0_216:
	s_mov_b32 s101, -1
	s_cmp_eq_u32 s65, 2
	s_cbranch_scc0 .Lb3_noovr
	s_cmp_eq_u32 s100, 1
	s_cbranch_scc0 .Lb3_noovr
	v_readfirstlane_b32 s1, v122
	s_nop 3
	s_cmp_lt_u32 s1, 2
	s_cbranch_scc0 .Lb3_noovr
	s_mov_b32 s64, 0
	v_add_u32_e32 v134, 0x300, v134
	s_mov_b32 s101, 0
.Lb3_noovr:
	s_add_i32 s0, s64, 63
	s_add_i32 s65, s65, 1
	v_cmp_le_u32_e32 vcc, s64, v126
	v_cmp_ge_u32_e64 s[0:1], s0, v128
	s_and_b32 s70, s65, 1
	s_and_b32 s70, s70, s101
	s_and_b64 s[72:73], vcc, s[0:1]
	s_waitcnt lgkmcnt(0)
	s_barrier
	s_and_saveexec_b64 s[0:1], s[72:73]
	s_cbranch_execz .LBB0_220
	s_mul_i32 s71, s70, 0x4800
	v_add_u32_e32 v98, s71, v125
	v_add3_u32 v38, v98, v127, v112
	v_add3_u32 v39, v98, v129, v112
	ds_read_b128 v[34:37], v38
	ds_read_b128 v[50:53], v38 offset:32
	ds_read_b128 v[54:57], v39
	ds_read_b128 v[136:139], v39 offset:32
	ds_read_b128 v[58:61], v38 offset:64
	ds_read_b128 v[62:65], v38 offset:96
	ds_read_b128 v[140:143], v39 offset:64
	ds_read_b128 v[144:147], v39 offset:96
	s_waitcnt lgkmcnt(0)
	v_mfma_f32_32x32x16_bf16 v[34:49], v[34:37], v[66:69], 0
	v_mfma_f32_32x32x16_bf16 v[34:49], v[50:53], v[70:73], v[34:49]
	v_add_u32_e32 v50, v98, v131
	v_add_u32_e32 v135, v50, v132
	ds_read_b64_tr_b16 v[102:103], v135 offset:9216
	ds_read_b64_tr_b16 v[104:105], v135 offset:10368
	ds_read_b64_tr_b16 v[100:101], v135 offset:10432
	ds_read_b64_tr_b16 v[98:99], v135 offset:9280
	v_mfma_f32_32x32x16_bf16 v[34:49], v[58:61], v[74:77], v[34:49]
	v_mfma_f32_32x32x16_bf16 v[34:49], v[62:65], v[78:81], v[34:49]
	v_mfma_f32_32x32x16_bf16 v[50:65], v[54:57], v[66:69], 0
	v_mfma_f32_32x32x16_bf16 v[50:65], v[136:139], v[70:73], v[50:65]
	ds_read2_b32 v[136:137], v134 offset0:58 offset1:59
	ds_read2_b32 v[138:139], v134 offset0:56 offset1:57
	ds_read2_b32 v[148:149], v134 offset0:50 offset1:51
	ds_read2_b32 v[150:151], v134 offset0:48 offset1:49
	ds_read2_b32 v[152:153], v134 offset0:26 offset1:27
	ds_read2_b32 v[154:155], v134 offset0:24 offset1:25
	ds_read2_b32 v[156:157], v134 offset0:18 offset1:19
	ds_read2_b32 v[158:159], v134 offset0:16 offset1:17
	v_mfma_f32_32x32x16_bf16 v[50:65], v[140:143], v[74:77], v[50:65]
	ds_read2_b32 v[140:141], v134 offset0:42 offset1:43
	ds_read2_b32 v[142:143], v134 offset0:40 offset1:41
	ds_read2_b32 v[160:161], v134 offset0:34 offset1:35
	ds_read2_b32 v[162:163], v134 offset0:32 offset1:33
	ds_read2_b32 v[164:165], v134 offset0:10 offset1:11
	ds_read2_b32 v[166:167], v134 offset0:8 offset1:9
	ds_read2_b32 v[168:169], v134 offset0:2 offset1:3
	ds_read2_b32 v[170:171], v134 offset1:1
	v_mfma_f32_32x32x16_bf16 v[50:65], v[144:147], v[78:81], v[50:65]
	s_nop 7
	s_nop 7
	s_nop 3
	s_waitcnt lgkmcnt(0)
	v_fma_f32 v137, v34, v178, v137
	v_fma_f32 v50, v50, v178, v153
	v_fma_f32 v35, v35, v178, v136
	v_fma_f32 v51, v51, v178, v152
	v_fma_f32 v36, v36, v178, v139
	v_fma_f32 v52, v52, v178, v155
	v_fma_f32 v37, v37, v178, v138
	v_fma_f32 v53, v53, v178, v154
	s_nop 0
	v_max3_f32 v34, v137, v35, v50
	v_fma_f32 v38, v38, v178, v149
	v_fma_f32 v39, v39, v178, v148
	v_fma_f32 v40, v40, v178, v151
	v_max3_f32 v136, v36, v37, v51
	v_fma_f32 v41, v41, v178, v150
	s_nop 0
	v_max3_f32 v34, v34, v52, v53
	v_fma_f32 v54, v54, v178, v157
	v_fma_f32 v55, v55, v178, v156
	v_fma_f32 v56, v56, v178, v159
	v_fma_f32 v57, v57, v178, v158
	v_max3_f32 v136, v136, v40, v41
	s_nop 0
	v_max3_f32 v34, v34, v38, v39
	v_fma_f32 v42, v42, v178, v141
	v_fma_f32 v43, v43, v178, v140
	v_fma_f32 v44, v44, v178, v143
	v_fma_f32 v45, v45, v178, v142
	v_max3_f32 v136, v136, v56, v57
	s_nop 0
	v_max3_f32 v34, v34, v54, v55
	v_fma_f32 v58, v58, v178, v165
	v_fma_f32 v59, v59, v178, v164
	v_fma_f32 v60, v60, v178, v167
	v_fma_f32 v61, v61, v178, v166
	v_max3_f32 v136, v136, v44, v45
	s_nop 0
	v_max3_f32 v34, v34, v42, v43
	v_fma_f32 v46, v46, v178, v161
	v_fma_f32 v47, v47, v178, v160
	v_fma_f32 v48, v48, v178, v163
	v_fma_f32 v49, v49, v178, v162
	v_max3_f32 v136, v136, v60, v61
	s_nop 0
	v_max3_f32 v34, v34, v58, v59
	v_fma_f32 v62, v62, v178, v169
	v_fma_f32 v63, v63, v178, v168
	v_fma_f32 v64, v64, v178, v171
	v_fma_f32 v65, v65, v178, v170
	v_max3_f32 v136, v136, v48, v49
	s_nop 0
	v_max3_f32 v34, v34, v46, v47
	s_nop 0
	v_max3_f32 v34, v34, v62, v63
	v_max3_f32 v136, v136, v64, v65
	s_nop 0
	v_max_f32_e32 v136, v136, v136
	v_max_f32_e32 v34, v34, v34
	v_max_f32_e32 v34, v34, v136
	v_mov_b32_e32 v136, v34
	s_nop 1
	v_permlane32_swap_b32_e32 v34, v136
	v_max_f32_e32 v136, v136, v136
	v_max_f32_e32 v34, v34, v34
	v_max_f32_e32 v34, v34, v136
	v_sub_f32_e32 v136, v34, v133
	v_cmp_lt_f32_e32 vcc, s45, v136
	s_cmp_eq_u64 vcc, 0
	v_max_f32_e32 v136, v133, v133
	v_max_f32_e32 v34, v136, v34
	s_cselect_b64 vcc, -1, 0
	v_cndmask_b32_e32 v34, v34, v133, vcc
	v_sub_f32 v136, v137, v34
	v_sub_f32 v50, v50, v34
	v_sub_f32 v51, v51, v34
	v_sub_f32 v36, v36, v34
	v_sub_f32 v52, v52, v34
	v_sub_f32 v53, v53, v34
	v_sub_f32 v54, v54, v34
	v_sub_f32 v39, v39, v34
	v_sub_f32 v55, v55, v34
	v_sub_f32 v40, v40, v34
	v_sub_f32 v56, v56, v34
	v_sub_f32 v57, v57, v34
	v_sub_f32 v58, v58, v34
	v_sub_f32 v43, v43, v34
	v_sub_f32 v44, v44, v34
	v_sub_f32 v47, v47, v34
	v_sub_f32 v48, v48, v34
	v_sub_f32 v137, v35, v34
	v_sub_f32 v138, v37, v34
	v_sub_f32 v139, v38, v34
	v_sub_f32 v140, v41, v34
	v_sub_f32 v141, v42, v34
	v_sub_f32 v142, v59, v34
	v_sub_f32 v143, v60, v34
	v_sub_f32 v144, v45, v34
	v_sub_f32 v145, v61, v34
	v_sub_f32 v146, v46, v34
	v_sub_f32 v147, v62, v34
	v_sub_f32 v148, v63, v34
	v_sub_f32 v149, v64, v34
	v_sub_f32 v150, v49, v34
	v_sub_f32 v151, v65, v34
	s_nop 0
	v_exp_f32_e32 v59, v136
	v_exp_f32_e32 v35, v50
	v_exp_f32_e32 v60, v137
	v_exp_f32_e32 v37, v51
	v_exp_f32_e32 v61, v36
	v_exp_f32_e32 v38, v52
	v_exp_f32_e32 v62, v138
	v_exp_f32_e32 v41, v53
	v_exp_f32_e32 v63, v139
	v_exp_f32_e32 v42, v54
	v_exp_f32_e32 v64, v39
	v_exp_f32_e32 v45, v55
	v_exp_f32_e32 v65, v40
	v_exp_f32_e32 v46, v56
	v_exp_f32_e32 v136, v140
	v_exp_f32_e32 v49, v57
	v_exp_f32_e32 v51, v141
	v_exp_f32_e32 v36, v58
	v_exp_f32_e32 v52, v43
	v_exp_f32_e32 v39, v142
	v_exp_f32_e32 v53, v44
	v_exp_f32_e32 v40, v143
	v_exp_f32_e32 v54, v144
	v_exp_f32_e32 v43, v145
	v_exp_f32_e32 v55, v146
	v_exp_f32_e32 v44, v147
	v_exp_f32_e32 v56, v47
	v_exp_f32_e32 v47, v148
	v_exp_f32_e32 v57, v48
	v_exp_f32_e32 v48, v149
	v_exp_f32_e32 v58, v150
	v_exp_f32_e32 v50, v151
	v_add_f32 v137, v59, v35
	v_add_f32 v138, v51, v36
	v_add_f32 v139, v52, v39
	v_add_f32 v140, v53, v40
	v_add_f32 v141, v54, v43
	v_add_f32 v142, v55, v44
	s_nop 1
	s_nop 0
	v_add_f32 v137, v137, v138
	v_add_f32 v138, v60, v37
	v_add_f32 v143, v56, v47
	v_add_f32 v144, v57, v48
	v_cmp_neq_f32_e32 vcc, v34, v133
	v_add_f32 v138, v138, v139
	v_add_f32 v139, v61, v38
	v_add_f32 v145, v58, v50
	s_nop 0
	v_add_f32 v139, v139, v140
	v_add_f32 v140, v62, v41
	v_add_f32 v137, v137, v138
	s_nop 0
	v_add_f32 v140, v140, v141
	v_add_f32 v141, v63, v42
	s_nop 0
	v_add_f32 v141, v141, v142
	v_add_f32 v142, v64, v45
	v_add_f32 v138, v139, v140
	s_nop 0
	v_add_f32 v142, v142, v143
	v_add_f32 v143, v65, v46
	v_add_f32 v137, v137, v138
	s_nop 0
	v_add_f32 v143, v143, v144
	v_add_f32 v144, v136, v49
	v_add_f32 v138, v141, v142
	s_nop 0
	v_add_f32 v144, v144, v145
	s_nop 0
	v_add_f32 v139, v143, v144
	s_nop 0
	v_add_f32 v138, v138, v139
	s_nop 0
	v_add_f32 v137, v137, v138
	s_cbranch_vccz .LBB0_219
	v_sub_f32_e32 v133, v133, v34
	v_exp_f32_e32 v138, v133
	s_nop 0
	v_mul_f32_e32 v124, v124, v138
	v_pk_mul_f32 v[32:33], v[32:33], v[138:139] op_sel_hi:[1,0]
	v_pk_mul_f32 v[30:31], v[30:31], v[138:139] op_sel_hi:[1,0]
	v_pk_mul_f32 v[28:29], v[28:29], v[138:139] op_sel_hi:[1,0]
	v_pk_mul_f32 v[26:27], v[26:27], v[138:139] op_sel_hi:[1,0]
	v_pk_mul_f32 v[24:25], v[24:25], v[138:139] op_sel_hi:[1,0]
	v_pk_mul_f32 v[22:23], v[22:23], v[138:139] op_sel_hi:[1,0]
	v_pk_mul_f32 v[20:21], v[20:21], v[138:139] op_sel_hi:[1,0]
	v_pk_mul_f32 v[18:19], v[18:19], v[138:139] op_sel_hi:[1,0]
	v_pk_mul_f32 v[16:17], v[16:17], v[138:139] op_sel_hi:[1,0]
	v_pk_mul_f32 v[14:15], v[14:15], v[138:139] op_sel_hi:[1,0]
	v_pk_mul_f32 v[12:13], v[12:13], v[138:139] op_sel_hi:[1,0]
	v_pk_mul_f32 v[10:11], v[10:11], v[138:139] op_sel_hi:[1,0]
	v_pk_mul_f32 v[8:9], v[8:9], v[138:139] op_sel_hi:[1,0]
	v_pk_mul_f32 v[6:7], v[6:7], v[138:139] op_sel_hi:[1,0]
	v_pk_mul_f32 v[4:5], v[4:5], v[138:139] op_sel_hi:[1,0]
	v_pk_mul_f32 v[2:3], v[2:3], v[138:139] op_sel_hi:[1,0]

; DI void band_item(const Params& P, char* lds_blk, int layer, int bp) {
;     ...
;     auto lstore = [&](int b) {
;         char* sK = lds + b * (2 * 64 * GP); char* sV = sK + 64 * GP;
; #pragma unroll
;         for (int j = 0; j < 2; ++j) { *(u32x4*)(sK + (srow + 32 * j) * GP + sch * 16) = rk[j]; *(u32x4*)(sV + (srow + 32 * j) * GP + sch * 16) = rv[j]; }
;     };
;     ...
;         if (kt + 1 < 4) lstore(b ^ 1);
;     }
.LBB0_220:
	s_or_b64 exec, exec, s[0:1]
	s_andn2_b64 vcc, exec, s[22:23]
	s_cbranch_vccnz .LBB0_213
	s_xor_b32 s0, s70, 1
	s_mulk_i32 s0, 0x4800
	v_add_u32_e32 v34, s0, v130
	s_waitcnt vmcnt(0)
	ds_write_b128 v34, v[82:85]
	ds_write_b128 v34, v[86:89] offset:9216
	ds_write_b128 v34, v[90:93] offset:4608
	ds_write_b128 v34, v[94:97] offset:13824
	s_cmp_eq_u32 s65, 2
	s_cbranch_scc0 .Lb3_nost0
	s_cmp_eq_u32 s100, 1
	s_cbranch_scc0 .Lb3_nost0
	s_waitcnt lgkmcnt(0)
	s_barrier
	ds_write_b128 v130, v[238:241]
	ds_write_b128 v130, v[242:245] offset:9216
	ds_write_b128 v130, v[246:249] offset:4608
	ds_write_b128 v130, v[250:253] offset:13824
.Lb3_nost0:
	s_branch .LBB0_213

; __global__ void __launch_bounds__(512, 1) mega(Params P) {
;     extern __shared__ __attribute__((aligned(16))) char lds[];
	.amdhsa_kernel _Z4mega6Params
		.amdhsa_group_segment_fixed_size 0
		.amdhsa_private_segment_fixed_size 0
		.amdhsa_kernarg_size 392
		.amdhsa_user_sgpr_count 2
		.amdhsa_user_sgpr_dispatch_ptr 0
		.amdhsa_user_sgpr_queue_ptr 0
		.amdhsa_user_sgpr_kernarg_segment_ptr 1
		.amdhsa_user_sgpr_dispatch_id 0
		.amdhsa_user_sgpr_kernarg_preload_length 0
		.amdhsa_user_sgpr_kernarg_preload_offset 0
		.amdhsa_user_sgpr_private_segment_size 0
		.amdhsa_uses_dynamic_stack 0
		.amdhsa_enable_private_segment 0
		.amdhsa_system_sgpr_workgroup_id_x 1
		.amdhsa_system_sgpr_workgroup_id_y 0
		.amdhsa_system_sgpr_workgroup_id_z 0
		.amdhsa_system_sgpr_workgroup_info 0
		.amdhsa_system_vgpr_workitem_id 2
		.amdhsa_next_free_vgpr 256
		.amdhsa_next_free_sgpr 102
		.amdhsa_accum_offset 256
		.amdhsa_reserve_vcc 1
		.amdhsa_float_round_mode_32 0
		.amdhsa_float_round_mode_16_64 0
		.amdhsa_float_denorm_mode_32 3
		.amdhsa_float_denorm_mode_16_64 3
		.amdhsa_dx10_clamp 1
		.amdhsa_ieee_mode 1
		.amdhsa_fp16_overflow 0
		.amdhsa_tg_split 0
		.amdhsa_exception_fp_ieee_invalid_op 0
		.amdhsa_exception_fp_denorm_src 0
		.amdhsa_exception_fp_ieee_div_zero 0
		.amdhsa_exception_fp_ieee_overflow 0
		.amdhsa_exception_fp_ieee_underflow 0
		.amdhsa_exception_fp_ieee_inexact 0
		.amdhsa_exception_int_div_zero 0
	.end_amdhsa_kernel

; __global__ void __launch_bounds__(512, 1) mega(Params P) {
;     extern __shared__ __attribute__((aligned(16))) char lds[];
amdhsa.kernels:
  - .agpr_count:     0
    .args:
      - .offset:         0
        .size:           136
        .value_kind:     by_value
      - .offset:         136
        .size:           4
        .value_kind:     hidden_block_count_x
      - .offset:         140
        .size:           4
        .value_kind:     hidden_block_count_y
      - .offset:         144
        .size:           4
        .value_kind:     hidden_block_count_z
      - .offset:         148
        .size:           2
        .value_kind:     hidden_group_size_x
      - .offset:         150
        .size:           2
        .value_kind:     hidden_group_size_y
      - .offset:         152
        .size:           2
        .value_kind:     hidden_group_size_z
      - .offset:         154
        .size:           2
        .value_kind:     hidden_remainder_x
      - .offset:         156
        .size:           2
        .value_kind:     hidden_remainder_y
      - .offset:         158
        .size:           2
        .value_kind:     hidden_remainder_z
      - .offset:         176
        .size:           8
        .value_kind:     hidden_global_offset_x
      - .offset:         184
        .size:           8
        .value_kind:     hidden_global_offset_y
      - .offset:         192
        .size:           8
        .value_kind:     hidden_global_offset_z
      - .offset:         200
        .size:           2
        .value_kind:     hidden_grid_dims
      - .offset:         224
        .size:           8
        .value_kind:     hidden_multigrid_sync_arg
      - .offset:         256
        .size:           4
        .value_kind:     hidden_dynamic_lds_size
    .group_segment_fixed_size: 0
    .kernarg_segment_align: 8
    .kernarg_segment_size: 392
    .language:       OpenCL C
    .language_version:
      - 2
      - 0
    .max_flat_workgroup_size: 512
    .name:           _Z4mega6Params
    .private_segment_fixed_size: 0
    .sgpr_count:     108
    .sgpr_spill_count: 118
    .symbol:         _Z4mega6Params.kd
    .uniform_work_group_size: 1
    .uses_dynamic_stack: false
    .vgpr_count:     256
    .vgpr_spill_count: 0
    .wavefront_size: 64
